# FFN-in GEMM K loop static priority raise built for the other wave half (waves 0-3 run the 2/1 copy) as the per-half comparison
# speedup vs baseline: 1.0014x; 1.0014x over previous
.LBB0_1705:
	s_ashr_i32 s45, s44, 31
	s_lshl_b64 s[12:13], s[44:45], 19
	s_add_u32 s12, s24, s12
	s_addc_u32 s13, s25, s13
	s_and_b64 s[34:35], s[38:39], exec
	s_cselect_b32 s37, s13, s49
	s_cselect_b32 s45, s12, s48
	s_ashr_i32 s41, s40, 31
	s_lshl_b64 s[34:35], s[40:41], 19
	s_add_u32 s34, s1, s34
	s_addc_u32 s35, s10, s35
	s_and_b64 s[50:51], s[38:39], exec
	s_cselect_b32 s41, s35, s27
	s_cselect_b32 s47, s34, s26
	s_add_u32 s48, s48, 0x40080
	s_addc_u32 s49, s49, 0
	s_add_u32 s52, s26, 0x100
	v_mov_b32_e32 v0, 0
	s_addc_u32 s53, s27, 0
	s_mov_b32 s64, -2
	v_mov_b32_e32 v1, v0
	v_mov_b32_e32 v2, v0
	v_mov_b32_e32 v3, v0
	v_mov_b32_e32 v8, v0
	v_mov_b32_e32 v9, v0
	v_mov_b32_e32 v10, v0
	v_mov_b32_e32 v11, v0
	v_mov_b32_e32 v16, v0
	v_mov_b32_e32 v17, v0
	v_mov_b32_e32 v18, v0
	v_mov_b32_e32 v19, v0
	v_mov_b32_e32 v24, v0
	v_mov_b32_e32 v25, v0
	v_mov_b32_e32 v26, v0
	v_mov_b32_e32 v27, v0
	v_mov_b32_e32 v32, v0
	v_mov_b32_e32 v33, v0
	v_mov_b32_e32 v34, v0
	v_mov_b32_e32 v35, v0
	v_mov_b32_e32 v40, v0
	v_mov_b32_e32 v41, v0
	v_mov_b32_e32 v42, v0
	v_mov_b32_e32 v43, v0
	v_mov_b32_e32 v52, v0
	v_mov_b32_e32 v53, v0
	v_mov_b32_e32 v54, v0
	v_mov_b32_e32 v55, v0
	v_mov_b32_e32 v60, v0
	v_mov_b32_e32 v61, v0
	v_mov_b32_e32 v62, v0
	v_mov_b32_e32 v63, v0
	v_mov_b32_e32 v4, v0
	v_mov_b32_e32 v5, v0
	v_mov_b32_e32 v6, v0
	v_mov_b32_e32 v7, v0
	v_mov_b32_e32 v12, v0
	v_mov_b32_e32 v13, v0
	v_mov_b32_e32 v14, v0
	v_mov_b32_e32 v15, v0
	v_mov_b32_e32 v20, v0
	v_mov_b32_e32 v21, v0
	v_mov_b32_e32 v22, v0
	v_mov_b32_e32 v23, v0
	v_mov_b32_e32 v28, v0
	v_mov_b32_e32 v29, v0
	v_mov_b32_e32 v30, v0
	v_mov_b32_e32 v31, v0
	v_mov_b32_e32 v36, v0
	v_mov_b32_e32 v37, v0
	v_mov_b32_e32 v38, v0
	v_mov_b32_e32 v39, v0
	v_mov_b32_e32 v44, v0
	v_mov_b32_e32 v45, v0
	v_mov_b32_e32 v46, v0
	v_mov_b32_e32 v47, v0
	v_mov_b32_e32 v56, v0
	v_mov_b32_e32 v57, v0
	v_mov_b32_e32 v58, v0
	v_mov_b32_e32 v59, v0
	v_mov_b32_e32 v64, v0
	v_mov_b32_e32 v65, v0
	v_mov_b32_e32 v66, v0
	v_mov_b32_e32 v67, v0
	v_mov_b32_e32 v68, v0
	v_mov_b32_e32 v69, v0
	v_mov_b32_e32 v70, v0
	v_mov_b32_e32 v71, v0
	v_mov_b32_e32 v76, v0
	v_mov_b32_e32 v77, v0
	v_mov_b32_e32 v78, v0
	v_mov_b32_e32 v79, v0
	v_mov_b32_e32 v84, v0
	v_mov_b32_e32 v85, v0
	v_mov_b32_e32 v86, v0
	v_mov_b32_e32 v87, v0
	v_mov_b32_e32 v92, v0
	v_mov_b32_e32 v93, v0
	v_mov_b32_e32 v94, v0
	v_mov_b32_e32 v95, v0
	v_mov_b32_e32 v100, v0
	v_mov_b32_e32 v101, v0
	v_mov_b32_e32 v102, v0
	v_mov_b32_e32 v103, v0
	v_mov_b32_e32 v108, v0
	v_mov_b32_e32 v109, v0
	v_mov_b32_e32 v110, v0
	v_mov_b32_e32 v111, v0
	v_mov_b32_e32 v116, v0
	v_mov_b32_e32 v117, v0
	v_mov_b32_e32 v118, v0
	v_mov_b32_e32 v119, v0
	v_mov_b32_e32 v124, v0
	v_mov_b32_e32 v125, v0
	v_mov_b32_e32 v126, v0
	v_mov_b32_e32 v127, v0
	v_mov_b32_e32 v72, v0
	v_mov_b32_e32 v73, v0
	v_mov_b32_e32 v74, v0
	v_mov_b32_e32 v75, v0
	v_mov_b32_e32 v80, v0
	v_mov_b32_e32 v81, v0
	v_mov_b32_e32 v82, v0
	v_mov_b32_e32 v83, v0
	v_mov_b32_e32 v88, v0
	v_mov_b32_e32 v89, v0
	v_mov_b32_e32 v90, v0
	v_mov_b32_e32 v91, v0
	v_mov_b32_e32 v96, v0
	v_mov_b32_e32 v97, v0
	v_mov_b32_e32 v98, v0
	v_mov_b32_e32 v99, v0
	v_mov_b32_e32 v104, v0
	v_mov_b32_e32 v105, v0
	v_mov_b32_e32 v106, v0
	v_mov_b32_e32 v107, v0
	v_mov_b32_e32 v112, v0
	v_mov_b32_e32 v113, v0
	v_mov_b32_e32 v114, v0
	v_mov_b32_e32 v115, v0
	v_mov_b32_e32 v120, v0
	v_mov_b32_e32 v121, v0
	v_mov_b32_e32 v122, v0
	v_mov_b32_e32 v123, v0
	v_mov_b32_e32 v128, v0
	v_mov_b32_e32 v129, v0
	v_mov_b32_e32 v130, v0
	v_mov_b32_e32 v131, v0
	s_and_b64 vcc, exec, s[6:7]
	s_cbranch_vccnz .Lgk2_1706
